# static wave priority per phase: waves 4-7 at s_setprio 1 in all tiled-GEMM phases (incl. gate, lora2), consumer waves 0-3 at 1 in the scan, 0 elsewhere
# baseline (speedup 1.0000x reference)
.LBB0_431:
	s_or_b64 exec, exec, s[0:1]
	s_cmpk_gt_i32 s2, 0x3ce
	s_waitcnt lgkmcnt(0)
	s_barrier
	s_cselect_b32 s99, 1, 0
	s_setprio 0
	v_readfirstlane_b32 s98, v174
	s_lshr_b32 s98, s98, 6
	s_cmp_ge_u32 s98, 4
	s_cbranch_scc0 .Lpr3_skip
	s_setprio 1
.Lpr3_skip:
	s_cmp_lg_u32 s99, 0
	s_cbranch_scc1 .LBB0_849
	s_add_u32 s36, s84, 0xfb588c0
	s_addc_u32 s37, s85, 0
	s_add_u32 s3, s84, 0x880000
	s_addc_u32 s15, s85, 0
	s_add_u32 s16, s84, 0x880100
	v_readlane_b32 s52, v192, 11
	s_addc_u32 s17, s85, 0
	s_add_i32 s40, s2, 0xfffffcf4
	s_add_i32 s41, s2, 0xfff4
	v_readlane_b32 s66, v192, 25
	v_readlane_b32 s53, v192, 12
	v_readlane_b32 s54, v192, 13
	v_readlane_b32 s55, v192, 14
	v_readlane_b32 s67, v192, 26
	s_add_u32 s46, s66, 0x218
	s_addc_u32 s48, s67, 0
	s_movk_i32 s49, 0x90
	s_mov_b32 s39, 0
	s_movk_i32 s45, 0x4080
	v_mov_b32_e32 v0, 0
	s_movk_i32 s47, 0x440
	s_movk_i32 s52, 0x880
	s_mov_b64 s[42:43], 0x80
	s_add_i32 s53, 0, 0x10000
	s_add_i32 s54, 0, 0x14000
	v_mov_b32_e32 v168, 0x4100
	v_mov_b32_e32 v169, 0x22000
	v_mov_b32_e32 v170, 0x88000
	s_mov_b32 s55, s2
	v_readlane_b32 s56, v192, 15
	v_readlane_b32 s57, v192, 16
	v_readlane_b32 s58, v192, 17
	v_readlane_b32 s59, v192, 18
	v_readlane_b32 s60, v192, 19
	v_readlane_b32 s61, v192, 20
	v_readlane_b32 s62, v192, 21
	v_readlane_b32 s63, v192, 22
	v_readlane_b32 s64, v192, 23
	v_readlane_b32 s65, v192, 24
	s_branch .LBB0_435

.LBB0_901:
	s_or_b64 exec, exec, s[0:1]
	s_mov_b32 s0, 0x8000
	v_cmp_gt_i32_e32 vcc, s0, v158
	s_waitcnt lgkmcnt(0)
	s_barrier
	s_cselect_b32 s99, 1, 0
	s_setprio 0
	v_readfirstlane_b32 s98, v174
	s_lshr_b32 s98, s98, 6
	s_cmp_ge_u32 s98, 4
	s_cbranch_scc0 .Lpr4_skip
	s_setprio 1
.Lpr4_skip:
	s_cmp_lg_u32 s99, 0
	s_and_saveexec_b64 s[0:1], vcc
	v_readlane_b32 s52, v192, 37
	v_readlane_b32 s54, v192, 39
	v_readlane_b32 s55, v192, 40
	v_readlane_b32 s53, v192, 38
	v_readlane_b32 s56, v192, 41
	v_readlane_b32 s57, v192, 42
	v_readlane_b32 s58, v192, 43
	v_readlane_b32 s59, v192, 44
	v_readlane_b32 s60, v192, 45
	v_readlane_b32 s61, v192, 46
	v_readlane_b32 s62, v192, 47
	v_readlane_b32 s63, v192, 48
	v_readlane_b32 s64, v192, 49
	v_readlane_b32 s65, v192, 50
	v_readlane_b32 s66, v192, 51
	v_readlane_b32 s67, v192, 52
	s_cbranch_execz .LBB0_904
	s_add_u32 s4, s82, 0x4000000
	s_addc_u32 s5, s83, 0
	s_ashr_i32 s15, s14, 31
	v_lshlrev_b64 v[0:1], 4, v[158:159]
	s_lshl_b64 s[6:7], s[14:15], 4
	s_mov_b64 s[8:9], 0
	s_movk_i32 s3, 0x7fff

.LBB0_1244:
	s_or_b64 exec, exec, s[0:1]
	s_cmpk_gt_i32 s2, 0x103
	s_waitcnt lgkmcnt(0)
	s_barrier
	s_cselect_b32 s99, 1, 0
	s_setprio 0
	v_readfirstlane_b32 s98, v174
	s_lshr_b32 s98, s98, 6
	s_cmp_ge_u32 s98, 4
	s_cbranch_scc0 .Lpr6_skip
	s_setprio 1
.Lpr6_skip:
	s_cmp_lg_u32 s99, 0
	s_cbranch_scc1 .LBB0_1273
	s_add_u32 s4, s84, 0xff688c0
	s_addc_u32 s5, s85, 0
	s_waitcnt vmcnt(22)
	v_mov_b32_e32 v1, 0
	s_mov_b32 s7, 0
	s_mov_b64 s[8:9], 0x80
	s_add_i32 s3, 0, 0x10000
	s_add_i32 s10, 0, 0x14000
	s_mov_b64 s[12:13], 0xc0
	s_add_i32 s11, 0, 0x4000
	s_movk_i32 s14, 0x4080
	s_movk_i32 s15, 0x880
	v_mov_b32_e32 v166, 0x3a27c5ac
	s_mov_b32 s16, 0x800000
	v_mbcnt_hi_u32_b32 v167, -1, v175
	v_mov_b32_e32 v168, 0x407f
	s_mov_b32 s17, s2
	s_branch .LBB0_1247

.LBB0_1325:
	s_or_b64 exec, exec, s[0:1]
	s_cmpk_lt_i32 s2, 0x140
	s_cselect_b64 s[4:5], -1, 0
	s_cmpk_gt_i32 s2, 0x13f
	s_waitcnt lgkmcnt(0)
	s_barrier
	s_cselect_b32 s99, 1, 0
	s_setprio 0
	v_readfirstlane_b32 s98, v174
	s_lshr_b32 s98, s98, 6
	s_cmp_ge_u32 s98, 4
	s_cbranch_scc0 .Lpr7_skip
	s_setprio 1
.Lpr7_skip:
	s_cmp_lg_u32 s99, 0
	s_cbranch_scc1 .LBB0_1468
	s_add_u32 s6, s84, 0x52a2880
	s_addc_u32 s7, s85, 0
	s_movk_i32 s3, 0x4000
	s_movk_i32 s16, 0x880
	s_waitcnt vmcnt(22)
	v_mov_b32_e32 v1, 0
	s_mov_b32 s9, 0
	s_movk_i32 s17, 0x6000
	s_add_i32 s18, 0, 0x10000
	s_add_i32 s19, 0, 0x14000
	s_movk_i32 s20, 0x4080
	s_mov_b32 s21, s2
	s_branch .LBB0_1328

.LBB0_1577:
	s_or_b64 exec, exec, s[0:1]
	s_cmpk_lt_i32 s2, 0x410
	s_cselect_b64 s[56:57], -1, 0
	s_cmpk_gt_i32 s2, 0x40f
	s_waitcnt lgkmcnt(0)
	s_barrier
	s_cselect_b32 s99, 1, 0
	s_setprio 0
	v_readfirstlane_b32 s98, v174
	s_lshr_b32 s98, s98, 6
	s_cmp_ge_u32 s98, 4
	s_cbranch_scc0 .Lpr9_skip
	s_setprio 1
.Lpr9_skip:
	s_cmp_lg_u32 s99, 0
	s_cbranch_scc1 .LBB0_1606
	v_readlane_b32 s0, v192, 53
	v_readlane_b32 s1, v192, 54
	s_movk_i32 s3, 0x880
	v_mov_b64_e32 v[158:159], s[88:89]
	v_mov_b64_e32 v[160:161], s[0:1]
	v_mov_b32_e32 v1, 0
	s_mov_b32 s7, 0
	s_mov_b64 s[8:9], 0x80
	s_add_i32 s10, 0, 0x10000
	s_add_i32 s11, 0, 0x14000
	s_movk_i32 s12, 0x4080
	s_movk_i32 s13, 0x2080
	s_mov_b32 s14, s2
	s_waitcnt vmcnt(0)
	s_branch .LBB0_1580

.LBB0_1658:
	s_or_b64 exec, exec, s[0:1]
	s_waitcnt lgkmcnt(0)
	v_cndmask_b32_e64 v0, 0, 1, s[4:5]
	v_cmp_ne_u32_e64 s[72:73], 1, v0
	s_andn2_b64 vcc, exec, s[4:5]
	s_barrier
	s_cselect_b32 s99, 1, 0
	s_setprio 0
	v_readfirstlane_b32 s98, v174
	s_lshr_b32 s98, s98, 6
	s_cmp_ge_u32 s98, 4
	s_cbranch_scc0 .Lpr10_skip
	s_setprio 1
.Lpr10_skip:
	s_cmp_lg_u32 s99, 0
	s_cbranch_vccnz .LBB0_1801
	s_add_u32 s4, s84, 0x52a5880
	s_addc_u32 s5, s85, 0
	s_movk_i32 s3, 0x4000
	s_movk_i32 s16, 0x2080
	v_mov_b32_e32 v1, 0
	s_mov_b32 s7, 0
	s_movk_i32 s17, 0x6000
	s_mov_b64 s[8:9], 0x80
	s_add_i32 s18, 0, 0x10000
	s_add_i32 s19, 0, 0x14000
	s_movk_i32 s20, 0x4080
	s_mov_b32 s21, s2
	s_branch .LBB0_1661

.LBB0_1910:
	s_or_b64 exec, exec, s[0:1]
	s_add_u32 s40, s84, 0x9d208c0
	s_addc_u32 s41, s85, 0
	s_add_u32 s58, s84, 0xa5408c0
	s_addc_u32 s59, s85, 0
	s_cmpk_gt_i32 s2, 0x185
	s_waitcnt lgkmcnt(0)
	s_barrier
	s_cselect_b32 s99, 1, 0
	s_setprio 0
	v_readfirstlane_b32 s98, v174
	s_lshr_b32 s98, s98, 6
	s_cmp_ge_u32 s98, 4
	s_cbranch_scc0 .Lpr12_skip
	s_setprio 1
.Lpr12_skip:
	s_cmp_lg_u32 s99, 0
	s_cbranch_scc1 .LBB0_2598
	s_add_u32 s16, s84, 0x58d0880
	s_addc_u32 s17, s85, 0
	s_add_u32 s20, s82, 0x7304000
	s_addc_u32 s21, s83, 0
	s_add_u32 s22, s82, 0x7284000
	s_addc_u32 s23, s83, 0
	s_add_u32 s24, s82, 0x6284000
	s_addc_u32 s25, s83, 0
	v_readlane_b32 s0, v192, 33
	s_add_u32 s26, s82, 0x6204000
	v_readlane_b32 s1, v192, 34
	s_addc_u32 s27, s83, 0
	s_movk_i32 s3, 0x880
	v_mov_b64_e32 v[158:159], s[88:89]
	v_mov_b64_e32 v[160:161], s[0:1]
	v_mov_b32_e32 v1, 0
	s_mov_b32 s19, 0
	s_movk_i32 s42, 0x2000
	s_movk_i32 s43, 0x4000
	s_mov_b64 s[28:29], 0x80
	s_add_i32 s44, 0, 0x10000
	s_add_i32 s45, 0, 0x14000
	s_movk_i32 s47, 0x3fff
	s_movk_i32 s52, 0x4080
	s_movk_i32 s53, 0xf7f
	s_movk_i32 s60, 0x7fff
	v_mov_b32_e32 v170, 0x10000
	v_mov_b32_e32 v171, 0x7f
	s_mov_b32 s61, s2
	s_branch .LBB0_1913

.LBB0_2750:
	s_or_b64 exec, exec, s[0:1]
	s_and_b64 vcc, exec, s[72:73]
	s_waitcnt lgkmcnt(0)
	s_barrier
	s_cselect_b32 s99, 1, 0
	s_setprio 0
	v_readfirstlane_b32 s98, v174
	s_lshr_b32 s98, s98, 6
	s_cmp_ge_u32 s98, 4
	s_cbranch_scc0 .Lpr14_skip
	s_setprio 1
.Lpr14_skip:
	s_cmp_lg_u32 s99, 0
	s_cbranch_vccnz .LBB0_2893
	s_add_u32 s4, s84, 0x52a2880
	s_addc_u32 s5, s85, 0
	s_movk_i32 s3, 0x4000
	s_movk_i32 s14, 0x880
	v_mov_b32_e32 v1, 0
	s_mov_b32 s7, 0
	s_movk_i32 s15, 0x6000
	s_add_i32 s16, 0, 0x10000
	s_add_i32 s17, 0, 0x14000
	s_movk_i32 s18, 0x4080
	s_mov_b32 s19, s2
	s_branch .LBB0_2753

.LBB0_3002:
	s_or_b64 exec, exec, s[0:1]
	v_readlane_b32 s52, v192, 55
	s_andn2_b64 vcc, exec, s[56:57]
	v_readlane_b32 s53, v192, 56
	s_waitcnt lgkmcnt(0)
	s_barrier
	s_cselect_b32 s99, 1, 0
	s_setprio 0
	v_readfirstlane_b32 s98, v174
	s_lshr_b32 s98, s98, 6
	s_cmp_ge_u32 s98, 4
	s_cbranch_scc0 .Lpr16_skip
	s_setprio 1
.Lpr16_skip:
	s_cmp_lg_u32 s99, 0
	s_cbranch_vccnz .LBB0_3031
	v_readlane_b32 s0, v192, 35
	v_readlane_b32 s1, v192, 36
	s_movk_i32 s3, 0x880
	v_mov_b64_e32 v[158:159], s[88:89]
	v_mov_b64_e32 v[160:161], s[0:1]
	v_mov_b32_e32 v1, 0
	s_mov_b32 s5, 0
	s_mov_b64 s[6:7], 0x80
	s_add_i32 s8, 0, 0x10000
	s_add_i32 s9, 0, 0x14000
	s_movk_i32 s10, 0x4080
	s_movk_i32 s11, 0x2080
	s_mov_b32 s12, s2
	s_waitcnt vmcnt(0)
	s_branch .LBB0_3005

.Lpr17_skip:
	s_cmp_lg_u32 s99, 0
	s_cbranch_vccnz .LBB0_3226
	s_add_u32 s4, s84, 0x52a5880
	s_addc_u32 s5, s85, 0
	s_movk_i32 s3, 0x4000
	s_movk_i32 s16, 0x2080
	v_mov_b32_e32 v1, 0
	s_mov_b32 s7, 0
	s_movk_i32 s17, 0x6000
	s_mov_b64 s[8:9], 0x80
	s_add_i32 s18, 0, 0x10000
	s_add_i32 s19, 0, 0x14000
	s_movk_i32 s20, 0x4080
	s_branch .LBB0_3086
